# hand-written S5 Bout row generation in prep (4+4 straight passes, gains/skip/powers fetched once) replacing compiled 8-pass branchy loop
# speedup vs baseline: 1.0055x; 1.0055x over previous
; __device__ __forceinline__ unsigned pk2(float lo, float hi) { return f2bf(lo) | (f2bf(hi) << 16); }
; __device__ __forceinline__ void s5_gen(LAS unsigned char* lds, const S5In P, int g, int q, bf16_t* Bst, bf16_t* Bout, const int tid) {
;     ...
;     for (int cid = tid; cid < 4096; cid += 512) { const int nl = cid >> 6, k0 = (cid & 63) * 8, n = q * 64 + nl, s = n >> 4, ch = n & 15; float v[8];
;         if (k0 < 256) { const int r = k0 >> 4, c0 = k0 & 15;
; #pragma unroll
;             for (int j = 0; j < 8; ++j) { const int c2 = c0 + j; float t = 0.f;
;                 if (r <= s) t += kt[((0 * 16 + (s - r)) * 16 + ch) * 16 + c2];
;                 if (r >= s) t += kt[((1 * 16 + (r - s)) * 16 + ch) * 16 + c2];
;                 if (r == s && c2 == ch) t += P.dskip[g * 16 + ch];
;                 v[j] = t * P.gain[g * 16 + c2]; }
;         } else { const int kk = k0 - 256, di = kk >> 7, ri = (kk >> 6) & 1, p0 = kk & 63;
; #pragma unroll
;             for (int j = 0; j < 8; ++j) { const int p = p0 + j; const f32x2v C = cc[(di * 16 + ch) * 64 + p], w = pw[(di * 64 + p) * 17 + (di == 0 ? s + 1 : 16 - s)];
;                 v[j] = ri == 0 ? (C.x * w.x - C.y * w.y) : -(C.x * w.y + C.y * w.x); } }
;         u32x4 o; o.x = pk2(v[0], v[1]); o.y = pk2(v[2], v[3]); o.z = pk2(v[4], v[5]); o.w = pk2(v[6], v[7]);
;         *(u32x4*)(Bout + ((size_t)g * 256 + n) * 512 + k0) = o; }
.LBB0_202:
	s_or_b64 exec, exec, s[28:29]
	s_and_saveexec_b64 s[28:29], s[40:41]
	s_cbranch_execz .LBB0_191
	s_ashr_i32 s17, s16, 31
	s_lshl_b32 s54, s48, 6
	s_lshl_b32 s30, s16, 4
	s_lshl_b64 s[16:17], s[16:17], 18
	s_add_u32 s16, s5, s16
	s_addc_u32 s17, s52, s17
	v_mbcnt_lo_u32_b32 v43, -1, 0
	v_mbcnt_hi_u32_b32 v43, -1, v43
	v_lshrrev_b32_e32 v44, 6, v66
	s_nop 0
	v_readfirstlane_b32 s42, v44
	v_lshrrev_b32_e32 v44, 5, v43
	v_and_b32_e32 v45, 31, v43
	v_and_b32_e32 v47, 1, v43
	v_lshlrev_b32_e32 v47, 3, v47
	v_add_u32_e32 v57, s30, v47
	v_lshlrev_b32_e32 v208, 2, v57
	v_lshl_add_u64 v[58:59], s[96:97], 0, v[208:209]
	global_load_dwordx4 v[6:9], v[58:59], off
	global_load_dwordx4 v[10:13], v[58:59], off offset:16
	v_and_b32_e32 v57, 15, v66
	v_lshrrev_b32_e32 v60, 4, v66
	v_add_u32_e32 v61, s30, v57
	v_lshlrev_b32_e32 v208, 2, v61
	v_lshl_add_u64 v[58:59], s[20:21], 0, v[208:209]
	global_load_dword v61, v[58:59], off
	s_lshr_b32 s43, s54, 4
	s_lshr_b32 s44, s42, 1
	s_add_i32 s43, s43, s44
	s_and_b32 s44, s42, 1
	s_lshl_b32 s44, s44, 3
	s_lshl_b32 s45, s42, 3
	s_add_i32 s45, s45, s54
	s_mov_b64 s[50:51], 0x800
	v_add_u32_e32 v46, s44, v44
	v_cmp_eq_u32_e32 vcc, v57, v60
	v_lshlrev_b32_e32 v60, 2, v66
	v_add_u32_e32 v60, 0x14400, v60
	s_waitcnt vmcnt(0)
	v_cndmask_b32_e32 v61, 0, v61, vcc
	ds_write_b32 v60, v61
	v_lshrrev_b32_e32 v57, 1, v45
	v_sub_u32_e32 v58, s43, v57
	v_subrev_u32_e32 v59, s43, v57
	v_lshlrev_b32_e32 v60, 6, v46
	v_lshl_add_u32 v60, v47, 2, v60
	v_lshl_add_u32 v52, v58, 10, v60
	v_add_u32_e32 v52, 0xc400, v52
	v_lshl_add_u32 v53, v59, 10, v60
	v_add_u32_e32 v53, 0x10400, v53
	v_add_u32_e32 v54, 0x14400, v60
	v_mov_b32_e32 v61, 0x14800
	v_cmp_le_i32_e32 vcc, 0, v58
	v_cndmask_b32_e32 v52, v61, v52, vcc
	v_cmp_le_i32_e32 vcc, 0, v59
	v_cndmask_b32_e32 v53, v61, v53, vcc
	v_cmp_eq_u32_e32 vcc, s43, v57
	v_cndmask_b32_e32 v54, v61, v54, vcc
	v_add_u32_e32 v57, s45, v44
	v_lshlrev_b32_e32 v57, 10, v57
	v_lshl_add_u32 v208, v45, 4, v57
	v_lshl_add_u64 v[48:49], s[16:17], 0, v[208:209]
	v_add_u32_e32 v208, 0x200, v208
	v_lshl_add_u64 v[50:51], s[16:17], 0, v[208:209]
	v_lshrrev_b32_e32 v57, 4, v45
	v_and_b32_e32 v58, 7, v45
	v_lshlrev_b32_e32 v58, 3, v58
	v_lshlrev_b32_e32 v55, 13, v57
	v_lshl_add_u32 v55, v46, 9, v55
	v_lshl_add_u32 v55, v58, 3, v55
	v_add_u32_e32 v55, 0x8400, v55
	s_add_i32 s46, s43, 1
	s_sub_i32 s47, 16, s43
	v_mov_b32_e32 v59, s47
	v_mov_b32_e32 v60, s46
	v_cmp_eq_u32_e32 vcc, 0, v57
	v_cndmask_b32_e32 v59, v59, v60, vcc
	v_lshl_add_u32 v56, v57, 6, v58
	v_mul_u32_u24_e32 v56, 0x88, v56
	v_lshl_add_u32 v56, v59, 3, v56
	v_and_b32_e32 v57, 8, v45
	v_cmp_eq_u32_e64 s[46:47], 0, v57
	s_waitcnt lgkmcnt(0)
	s_barrier
	ds_read_b128 v[14:17], v52 offset:0
	ds_read_b128 v[18:21], v52 offset:16
	ds_read_b128 v[22:25], v53 offset:0
	ds_read_b128 v[26:29], v53 offset:16
	ds_read_b128 v[30:33], v54 offset:0
	ds_read_b128 v[0:3], v54 offset:16
	s_waitcnt lgkmcnt(2)
	v_pk_add_f32 v[14:15], v[14:15], v[22:23]
	v_pk_add_f32 v[16:17], v[16:17], v[24:25]
	v_pk_add_f32 v[18:19], v[18:19], v[26:27]
	v_pk_add_f32 v[20:21], v[20:21], v[28:29]
	s_waitcnt lgkmcnt(0)
	v_pk_add_f32 v[14:15], v[14:15], v[30:31]
	v_pk_add_f32 v[16:17], v[16:17], v[32:33]
	v_pk_add_f32 v[18:19], v[18:19], v[0:1]
	v_pk_add_f32 v[20:21], v[20:21], v[2:3]
	v_pk_mul_f32 v[14:15], v[14:15], v[6:7]
	v_pk_mul_f32 v[16:17], v[16:17], v[8:9]
	v_pk_mul_f32 v[18:19], v[18:19], v[10:11]
	v_pk_mul_f32 v[20:21], v[20:21], v[12:13]
	v_cvt_pk_bf16_f32 v22, v14, v15
	v_cvt_pk_bf16_f32 v23, v16, v17
	v_cvt_pk_bf16_f32 v24, v18, v19
	v_cvt_pk_bf16_f32 v25, v20, v21
	global_store_dwordx4 v[48:49], v[22:25], off
	s_nop 1
	v_lshl_add_u64 v[48:49], v[48:49], 0, s[50:51]
	ds_read_b128 v[14:17], v52 offset:128
	ds_read_b128 v[18:21], v52 offset:144
	ds_read_b128 v[22:25], v53 offset:128
	ds_read_b128 v[26:29], v53 offset:144
	ds_read_b128 v[30:33], v54 offset:128
	ds_read_b128 v[0:3], v54 offset:144
	s_waitcnt lgkmcnt(2)
	v_pk_add_f32 v[14:15], v[14:15], v[22:23]
	v_pk_add_f32 v[16:17], v[16:17], v[24:25]
	v_pk_add_f32 v[18:19], v[18:19], v[26:27]
	v_pk_add_f32 v[20:21], v[20:21], v[28:29]
	s_waitcnt lgkmcnt(0)
	v_pk_add_f32 v[14:15], v[14:15], v[30:31]
	v_pk_add_f32 v[16:17], v[16:17], v[32:33]
	v_pk_add_f32 v[18:19], v[18:19], v[0:1]
	v_pk_add_f32 v[20:21], v[20:21], v[2:3]
	v_pk_mul_f32 v[14:15], v[14:15], v[6:7]
	v_pk_mul_f32 v[16:17], v[16:17], v[8:9]
	v_pk_mul_f32 v[18:19], v[18:19], v[10:11]
	v_pk_mul_f32 v[20:21], v[20:21], v[12:13]
	v_cvt_pk_bf16_f32 v22, v14, v15
	v_cvt_pk_bf16_f32 v23, v16, v17
	v_cvt_pk_bf16_f32 v24, v18, v19
	v_cvt_pk_bf16_f32 v25, v20, v21
	global_store_dwordx4 v[48:49], v[22:25], off
	s_nop 1
	v_lshl_add_u64 v[48:49], v[48:49], 0, s[50:51]
	ds_read_b128 v[14:17], v52 offset:256
	ds_read_b128 v[18:21], v52 offset:272
	ds_read_b128 v[22:25], v53 offset:256
	ds_read_b128 v[26:29], v53 offset:272
	ds_read_b128 v[30:33], v54 offset:256
	ds_read_b128 v[0:3], v54 offset:272
	s_waitcnt lgkmcnt(2)
	v_pk_add_f32 v[14:15], v[14:15], v[22:23]
	v_pk_add_f32 v[16:17], v[16:17], v[24:25]
	v_pk_add_f32 v[18:19], v[18:19], v[26:27]
	v_pk_add_f32 v[20:21], v[20:21], v[28:29]
	s_waitcnt lgkmcnt(0)
	v_pk_add_f32 v[14:15], v[14:15], v[30:31]
	v_pk_add_f32 v[16:17], v[16:17], v[32:33]
	v_pk_add_f32 v[18:19], v[18:19], v[0:1]
	v_pk_add_f32 v[20:21], v[20:21], v[2:3]
	v_pk_mul_f32 v[14:15], v[14:15], v[6:7]
	v_pk_mul_f32 v[16:17], v[16:17], v[8:9]
	v_pk_mul_f32 v[18:19], v[18:19], v[10:11]
	v_pk_mul_f32 v[20:21], v[20:21], v[12:13]
	v_cvt_pk_bf16_f32 v22, v14, v15
	v_cvt_pk_bf16_f32 v23, v16, v17
	v_cvt_pk_bf16_f32 v24, v18, v19
	v_cvt_pk_bf16_f32 v25, v20, v21
	global_store_dwordx4 v[48:49], v[22:25], off
	s_nop 1
	v_lshl_add_u64 v[48:49], v[48:49], 0, s[50:51]
	ds_read_b128 v[14:17], v52 offset:384
	ds_read_b128 v[18:21], v52 offset:400
	ds_read_b128 v[22:25], v53 offset:384
	ds_read_b128 v[26:29], v53 offset:400
	ds_read_b128 v[30:33], v54 offset:384
	ds_read_b128 v[0:3], v54 offset:400
	s_waitcnt lgkmcnt(2)
; __device__ __forceinline__ unsigned pk2(float lo, float hi) { return f2bf(lo) | (f2bf(hi) << 16); }
; __device__ __forceinline__ void s5_gen(LAS unsigned char* lds, const S5In P, int g, int q, bf16_t* Bst, bf16_t* Bout, const int tid) {
;     ...
;         } else { const int kk = k0 - 256, di = kk >> 7, ri = (kk >> 6) & 1, p0 = kk & 63;
; #pragma unroll
;             for (int j = 0; j < 8; ++j) { const int p = p0 + j; const f32x2v C = cc[(di * 16 + ch) * 64 + p], w = pw[(di * 64 + p) * 17 + (di == 0 ? s + 1 : 16 - s)];
;                 v[j] = ri == 0 ? (C.x * w.x - C.y * w.y) : -(C.x * w.y + C.y * w.x); } }
;         u32x4 o; o.x = pk2(v[0], v[1]); o.y = pk2(v[2], v[3]); o.z = pk2(v[4], v[5]); o.w = pk2(v[6], v[7]);
;         *(u32x4*)(Bout + ((size_t)g * 256 + n) * 512 + k0) = o; }
	v_pk_add_f32 v[14:15], v[14:15], v[22:23]
	v_pk_add_f32 v[16:17], v[16:17], v[24:25]
	v_pk_add_f32 v[18:19], v[18:19], v[26:27]
	v_pk_add_f32 v[20:21], v[20:21], v[28:29]
	s_waitcnt lgkmcnt(0)
	v_pk_add_f32 v[14:15], v[14:15], v[30:31]
	v_pk_add_f32 v[16:17], v[16:17], v[32:33]
	v_pk_add_f32 v[18:19], v[18:19], v[0:1]
	v_pk_add_f32 v[20:21], v[20:21], v[2:3]
	v_pk_mul_f32 v[14:15], v[14:15], v[6:7]
	v_pk_mul_f32 v[16:17], v[16:17], v[8:9]
	v_pk_mul_f32 v[18:19], v[18:19], v[10:11]
	v_pk_mul_f32 v[20:21], v[20:21], v[12:13]
	v_cvt_pk_bf16_f32 v22, v14, v15
	v_cvt_pk_bf16_f32 v23, v16, v17
	v_cvt_pk_bf16_f32 v24, v18, v19
	v_cvt_pk_bf16_f32 v25, v20, v21
	global_store_dwordx4 v[48:49], v[22:25], off
	s_nop 1
	ds_read_b64 v[6:7], v56
	ds_read_b64 v[8:9], v56 offset:136
	ds_read_b64 v[10:11], v56 offset:272
	ds_read_b64 v[12:13], v56 offset:408
	ds_read_b64 v[14:15], v56 offset:544
	ds_read_b64 v[16:17], v56 offset:680
	ds_read_b64 v[18:19], v56 offset:816
	ds_read_b64 v[20:21], v56 offset:952
	ds_read_b128 v[22:25], v55 offset:0
	ds_read_b128 v[26:29], v55 offset:16
	ds_read_b128 v[30:33], v55 offset:32
	ds_read_b128 v[0:3], v55 offset:48
	s_waitcnt lgkmcnt(0)
	v_mul_f32_e32 v4, v23, v7
	v_mul_f32_e32 v5, v23, v6
	v_fma_f32 v4, v22, v6, -v4
	v_fma_f32 v5, v22, v7, v5
	v_cndmask_b32_e64 v22, -v5, v4, s[46:47]
	v_mul_f32_e32 v4, v25, v9
	v_mul_f32_e32 v5, v25, v8
	v_fma_f32 v4, v24, v8, -v4
	v_fma_f32 v5, v24, v9, v5
	v_cndmask_b32_e64 v24, -v5, v4, s[46:47]
	v_mul_f32_e32 v4, v27, v11
	v_mul_f32_e32 v5, v27, v10
	v_fma_f32 v4, v26, v10, -v4
	v_fma_f32 v5, v26, v11, v5
	v_cndmask_b32_e64 v26, -v5, v4, s[46:47]
	v_mul_f32_e32 v4, v29, v13
	v_mul_f32_e32 v5, v29, v12
	v_fma_f32 v4, v28, v12, -v4
	v_fma_f32 v5, v28, v13, v5
	v_cndmask_b32_e64 v28, -v5, v4, s[46:47]
	v_mul_f32_e32 v4, v31, v15
	v_mul_f32_e32 v5, v31, v14
	v_fma_f32 v4, v30, v14, -v4
	v_fma_f32 v5, v30, v15, v5
	v_cndmask_b32_e64 v30, -v5, v4, s[46:47]
	v_mul_f32_e32 v4, v33, v17
	v_mul_f32_e32 v5, v33, v16
	v_fma_f32 v4, v32, v16, -v4
	v_fma_f32 v5, v32, v17, v5
	v_cndmask_b32_e64 v32, -v5, v4, s[46:47]
	v_mul_f32_e32 v4, v1, v19
	v_mul_f32_e32 v5, v1, v18
	v_fma_f32 v4, v0, v18, -v4
	v_fma_f32 v5, v0, v19, v5
	v_cndmask_b32_e64 v0, -v5, v4, s[46:47]
	v_mul_f32_e32 v4, v3, v21
	v_mul_f32_e32 v5, v3, v20
	v_fma_f32 v4, v2, v20, -v4
	v_fma_f32 v5, v2, v21, v5
	v_cndmask_b32_e64 v2, -v5, v4, s[46:47]
	v_cvt_pk_bf16_f32 v58, v22, v24
	v_cvt_pk_bf16_f32 v59, v26, v28
	v_cvt_pk_bf16_f32 v60, v30, v32
	v_cvt_pk_bf16_f32 v61, v0, v2
	global_store_dwordx4 v[50:51], v[58:61], off
	s_nop 1
	v_lshl_add_u64 v[50:51], v[50:51], 0, s[50:51]
	ds_read_b128 v[22:25], v55 offset:1024
	ds_read_b128 v[26:29], v55 offset:1040
	ds_read_b128 v[30:33], v55 offset:1056
	ds_read_b128 v[0:3], v55 offset:1072
	s_waitcnt lgkmcnt(0)
	v_mul_f32_e32 v4, v23, v7
	v_mul_f32_e32 v5, v23, v6
	v_fma_f32 v4, v22, v6, -v4
	v_fma_f32 v5, v22, v7, v5
	v_cndmask_b32_e64 v22, -v5, v4, s[46:47]
	v_mul_f32_e32 v4, v25, v9
	v_mul_f32_e32 v5, v25, v8
	v_fma_f32 v4, v24, v8, -v4
	v_fma_f32 v5, v24, v9, v5
	v_cndmask_b32_e64 v24, -v5, v4, s[46:47]
	v_mul_f32_e32 v4, v27, v11
	v_mul_f32_e32 v5, v27, v10
	v_fma_f32 v4, v26, v10, -v4
	v_fma_f32 v5, v26, v11, v5
	v_cndmask_b32_e64 v26, -v5, v4, s[46:47]
	v_mul_f32_e32 v4, v29, v13
	v_mul_f32_e32 v5, v29, v12
	v_fma_f32 v4, v28, v12, -v4
	v_fma_f32 v5, v28, v13, v5
	v_cndmask_b32_e64 v28, -v5, v4, s[46:47]
	v_mul_f32_e32 v4, v31, v15
	v_mul_f32_e32 v5, v31, v14
	v_fma_f32 v4, v30, v14, -v4
	v_fma_f32 v5, v30, v15, v5
	v_cndmask_b32_e64 v30, -v5, v4, s[46:47]
	v_mul_f32_e32 v4, v33, v17
	v_mul_f32_e32 v5, v33, v16
	v_fma_f32 v4, v32, v16, -v4
	v_fma_f32 v5, v32, v17, v5
	v_cndmask_b32_e64 v32, -v5, v4, s[46:47]
	v_mul_f32_e32 v4, v1, v19
	v_mul_f32_e32 v5, v1, v18
	v_fma_f32 v4, v0, v18, -v4
	v_fma_f32 v5, v0, v19, v5
	v_cndmask_b32_e64 v0, -v5, v4, s[46:47]
	v_mul_f32_e32 v4, v3, v21
	v_mul_f32_e32 v5, v3, v20
	v_fma_f32 v4, v2, v20, -v4
	v_fma_f32 v5, v2, v21, v5
	v_cndmask_b32_e64 v2, -v5, v4, s[46:47]
	v_cvt_pk_bf16_f32 v58, v22, v24
	v_cvt_pk_bf16_f32 v59, v26, v28
	v_cvt_pk_bf16_f32 v60, v30, v32
	v_cvt_pk_bf16_f32 v61, v0, v2
	global_store_dwordx4 v[50:51], v[58:61], off
	s_nop 1
	v_lshl_add_u64 v[50:51], v[50:51], 0, s[50:51]
	ds_read_b128 v[22:25], v55 offset:2048
	ds_read_b128 v[26:29], v55 offset:2064
	ds_read_b128 v[30:33], v55 offset:2080
	ds_read_b128 v[0:3], v55 offset:2096
	s_waitcnt lgkmcnt(0)
; __device__ __forceinline__ unsigned pk2(float lo, float hi) { return f2bf(lo) | (f2bf(hi) << 16); }
; __device__ __forceinline__ void s5_gen(LAS unsigned char* lds, const S5In P, int g, int q, bf16_t* Bst, bf16_t* Bout, const int tid) {
;     ...
;         } else { const int kk = k0 - 256, di = kk >> 7, ri = (kk >> 6) & 1, p0 = kk & 63;
; #pragma unroll
;             for (int j = 0; j < 8; ++j) { const int p = p0 + j; const f32x2v C = cc[(di * 16 + ch) * 64 + p], w = pw[(di * 64 + p) * 17 + (di == 0 ? s + 1 : 16 - s)];
;                 v[j] = ri == 0 ? (C.x * w.x - C.y * w.y) : -(C.x * w.y + C.y * w.x); } }
;         u32x4 o; o.x = pk2(v[0], v[1]); o.y = pk2(v[2], v[3]); o.z = pk2(v[4], v[5]); o.w = pk2(v[6], v[7]);
;         *(u32x4*)(Bout + ((size_t)g * 256 + n) * 512 + k0) = o; }
	v_mul_f32_e32 v4, v23, v7
	v_mul_f32_e32 v5, v23, v6
	v_fma_f32 v4, v22, v6, -v4
	v_fma_f32 v5, v22, v7, v5
	v_cndmask_b32_e64 v22, -v5, v4, s[46:47]
	v_mul_f32_e32 v4, v25, v9
	v_mul_f32_e32 v5, v25, v8
	v_fma_f32 v4, v24, v8, -v4
	v_fma_f32 v5, v24, v9, v5
	v_cndmask_b32_e64 v24, -v5, v4, s[46:47]
	v_mul_f32_e32 v4, v27, v11
	v_mul_f32_e32 v5, v27, v10
	v_fma_f32 v4, v26, v10, -v4
	v_fma_f32 v5, v26, v11, v5
	v_cndmask_b32_e64 v26, -v5, v4, s[46:47]
	v_mul_f32_e32 v4, v29, v13
	v_mul_f32_e32 v5, v29, v12
	v_fma_f32 v4, v28, v12, -v4
	v_fma_f32 v5, v28, v13, v5
	v_cndmask_b32_e64 v28, -v5, v4, s[46:47]
	v_mul_f32_e32 v4, v31, v15
	v_mul_f32_e32 v5, v31, v14
	v_fma_f32 v4, v30, v14, -v4
	v_fma_f32 v5, v30, v15, v5
	v_cndmask_b32_e64 v30, -v5, v4, s[46:47]
	v_mul_f32_e32 v4, v33, v17
	v_mul_f32_e32 v5, v33, v16
	v_fma_f32 v4, v32, v16, -v4
	v_fma_f32 v5, v32, v17, v5
	v_cndmask_b32_e64 v32, -v5, v4, s[46:47]
	v_mul_f32_e32 v4, v1, v19
	v_mul_f32_e32 v5, v1, v18
	v_fma_f32 v4, v0, v18, -v4
	v_fma_f32 v5, v0, v19, v5
	v_cndmask_b32_e64 v0, -v5, v4, s[46:47]
	v_mul_f32_e32 v4, v3, v21
	v_mul_f32_e32 v5, v3, v20
	v_fma_f32 v4, v2, v20, -v4
	v_fma_f32 v5, v2, v21, v5
	v_cndmask_b32_e64 v2, -v5, v4, s[46:47]
	v_cvt_pk_bf16_f32 v58, v22, v24
	v_cvt_pk_bf16_f32 v59, v26, v28
	v_cvt_pk_bf16_f32 v60, v30, v32
	v_cvt_pk_bf16_f32 v61, v0, v2
	global_store_dwordx4 v[50:51], v[58:61], off
	s_nop 1
	v_lshl_add_u64 v[50:51], v[50:51], 0, s[50:51]
	ds_read_b128 v[22:25], v55 offset:3072
	ds_read_b128 v[26:29], v55 offset:3088
	ds_read_b128 v[30:33], v55 offset:3104
	ds_read_b128 v[0:3], v55 offset:3120
	s_waitcnt lgkmcnt(0)
	v_mul_f32_e32 v4, v23, v7
	v_mul_f32_e32 v5, v23, v6
	v_fma_f32 v4, v22, v6, -v4
	v_fma_f32 v5, v22, v7, v5
	v_cndmask_b32_e64 v22, -v5, v4, s[46:47]
	v_mul_f32_e32 v4, v25, v9
	v_mul_f32_e32 v5, v25, v8
	v_fma_f32 v4, v24, v8, -v4
	v_fma_f32 v5, v24, v9, v5
	v_cndmask_b32_e64 v24, -v5, v4, s[46:47]
	v_mul_f32_e32 v4, v27, v11
	v_mul_f32_e32 v5, v27, v10
	v_fma_f32 v4, v26, v10, -v4
	v_fma_f32 v5, v26, v11, v5
	v_cndmask_b32_e64 v26, -v5, v4, s[46:47]
	v_mul_f32_e32 v4, v29, v13
	v_mul_f32_e32 v5, v29, v12
	v_fma_f32 v4, v28, v12, -v4
	v_fma_f32 v5, v28, v13, v5
	v_cndmask_b32_e64 v28, -v5, v4, s[46:47]
	v_mul_f32_e32 v4, v31, v15
	v_mul_f32_e32 v5, v31, v14
	v_fma_f32 v4, v30, v14, -v4
	v_fma_f32 v5, v30, v15, v5
	v_cndmask_b32_e64 v30, -v5, v4, s[46:47]
	v_mul_f32_e32 v4, v33, v17
	v_mul_f32_e32 v5, v33, v16
	v_fma_f32 v4, v32, v16, -v4
	v_fma_f32 v5, v32, v17, v5
	v_cndmask_b32_e64 v32, -v5, v4, s[46:47]
	v_mul_f32_e32 v4, v1, v19
	v_mul_f32_e32 v5, v1, v18
	v_fma_f32 v4, v0, v18, -v4
	v_fma_f32 v5, v0, v19, v5
	v_cndmask_b32_e64 v0, -v5, v4, s[46:47]
	v_mul_f32_e32 v4, v3, v21
	v_mul_f32_e32 v5, v3, v20
	v_fma_f32 v4, v2, v20, -v4
	v_fma_f32 v5, v2, v21, v5
	v_cndmask_b32_e64 v2, -v5, v4, s[46:47]
	v_cvt_pk_bf16_f32 v58, v22, v24
	v_cvt_pk_bf16_f32 v59, v26, v28
	v_cvt_pk_bf16_f32 v60, v30, v32
	v_cvt_pk_bf16_f32 v61, v0, v2
	global_store_dwordx4 v[50:51], v[58:61], off
	s_nop 1
	s_branch .LBB0_191
